# MA Fourier-combine path: the row's four x-piece loads issued together (prefetch registers) instead of one per piece; on top of MA row/weight staging batching
# speedup vs baseline: 1.0083x; 1.0083x over previous
; #define GAS __attribute__((address_space(1)))
; __device__ __forceinline__ void phase_ma(const Params& p, Frame& F, int l, const bool fd, const float* xin32) {
;     ...
;             for (int j = 0; j < 4; ++j) { if (!fd) { const v2u xw = *(const GAS v2u*)(xb + (size_t)row * D + 256 * j + 4 * F.lane); h[r][j] = (f32x4){bf_lo(xw.x), bf_hi(xw.x), bf_lo(xw.y), bf_hi(xw.y)}; } ss += (h[r][j].x * h[r][j].x + h[r][j].y * h[r][j].y) + (h[r][j].z * h[r][j].z + h[r][j].w * h[r][j].w); }
.LBB0_615:
	s_waitcnt lgkmcnt(0)
	global_load_dwordx2 v[194:195], v[32:33], off
	global_load_dwordx2 v[196:197], v[32:33], off offset:512
	global_load_dwordx2 v[198:199], v[32:33], off offset:1024
	global_load_dwordx2 v[200:201], v[32:33], off offset:1536
	s_add_i32 vcc_lo, s54, s4
	s_lshl_b32 vcc_lo, vcc_lo, 11
	s_mov_b32 vcc_hi, 0
	v_lshl_add_u64 v[226:227], v[52:53], 0, vcc
	global_load_dwordx2 v[202:203], v[226:227], off
	global_load_dwordx2 v[204:205], v[226:227], off offset:512
	global_load_dwordx2 v[206:207], v[226:227], off offset:1024
	global_load_dwordx2 v[208:209], v[226:227], off offset:1536
	s_add_i32 vcc_lo, s53, s4
	s_lshl_b32 vcc_lo, vcc_lo, 11
	s_mov_b32 vcc_hi, 0
	v_lshl_add_u64 v[228:229], v[52:53], 0, vcc
	global_load_dwordx2 v[210:211], v[228:229], off
	global_load_dwordx2 v[212:213], v[228:229], off offset:512
	global_load_dwordx2 v[214:215], v[228:229], off offset:1024
	global_load_dwordx2 v[216:217], v[228:229], off offset:1536
	s_add_i32 vcc_lo, s5, s4
	s_lshl_b32 vcc_lo, vcc_lo, 11
	s_mov_b32 vcc_hi, 0
	v_lshl_add_u64 v[230:231], v[52:53], 0, vcc
	global_load_dwordx2 v[218:219], v[230:231], off
	global_load_dwordx2 v[220:221], v[230:231], off offset:512
	global_load_dwordx2 v[222:223], v[230:231], off offset:1024
	global_load_dwordx2 v[224:225], v[230:231], off offset:1536
	s_waitcnt vmcnt(0)
	v_mov_b32_e32 v34, v194
	v_mov_b32_e32 v35, v195
	s_nop 0
	v_lshlrev_b32_e32 v78, 16, v34
	v_and_b32_e32 v79, 0xffff0000, v34
	v_lshlrev_b32_e32 v112, 16, v35
	v_and_b32_e32 v113, 0xffff0000, v35
	s_and_b64 vcc, exec, s[48:49]
	s_cbranch_vccz .LBB0_666

; #define GAS __attribute__((address_space(1)))
; __device__ __forceinline__ void phase_ma(const Params& p, Frame& F, int l, const bool fd, const float* xin32) {
;     ...
;             for (int j = 0; j < 4; ++j) { if (!fd) { const v2u xw = *(const GAS v2u*)(xb + (size_t)row * D + 256 * j + 4 * F.lane); h[r][j] = (f32x4){bf_lo(xw.x), bf_hi(xw.x), bf_lo(xw.y), bf_hi(xw.y)}; } ss += (h[r][j].x * h[r][j].x + h[r][j].y * h[r][j].y) + (h[r][j].z * h[r][j].z + h[r][j].w * h[r][j].w); }
.LBB0_617:
	s_waitcnt lgkmcnt(0)
	s_waitcnt vmcnt(0)
	v_mov_b32_e32 v34, v198
	v_mov_b32_e32 v35, v199
	s_nop 0
	v_lshlrev_b32_e32 v68, 16, v34
	v_and_b32_e32 v69, 0xffff0000, v34
	v_lshlrev_b32_e32 v96, 16, v35
	v_and_b32_e32 v97, 0xffff0000, v35
	s_and_b64 vcc, exec, s[48:49]
	s_cbranch_vccnz .LBB0_669
	s_branch .LBB0_668

; #define GAS __attribute__((address_space(1)))
; __device__ __forceinline__ void phase_ma(const Params& p, Frame& F, int l, const bool fd, const float* xin32) {
;     ...
;                     if (special) y = *(const f32x4*)(y4096 + b * 1024 + cc); else { const v2u pw = *(const GAS v2u*)(P + cc), qw = *(const GAS v2u*)(P + 1024 + cc);
;                         y.x = bf_lo(pw.x) + sg * bf_lo(qw.x); y.y = bf_hi(pw.x) + sg * bf_hi(qw.x); y.z = bf_lo(pw.y) + sg * bf_lo(qw.y); y.w = bf_hi(pw.y) + sg * bf_hi(qw.y); }
;                     f32x4 xo; if (xin32) xo = *(const GAS f32x4*)(xin32 + (size_t)row * D + cc); else { const v2u xw = *(const GAS v2u*)(xb + (size_t)row * D + cc); xo = (f32x4){bf_lo(xw.x), bf_hi(xw.x), bf_lo(xw.y), bf_hi(xw.y)}; }
.LBB0_634:
	s_andn2_b64 vcc, exec, s[16:17]
	s_cbranch_vccnz .LBB0_636
	s_waitcnt lgkmcnt(0)
	flat_load_dwordx4 v[32:35], v[54:55]
	s_waitcnt vmcnt(0) lgkmcnt(0)
.LBB0_636:
	s_ashr_i32 s3, s2, 31
	s_lshl_b64 s[8:9], s[2:3], 11
	s_add_u32 s16, s6, s8
	s_addc_u32 s17, s7, s9
	s_lshl_b64 s[2:3], s[2:3], 12
	v_lshl_add_u64 v[36:37], v[64:65], 0, s[2:3]
	v_lshl_add_u64 v[70:71], v[66:67], 2, v[36:37]
	s_cmp_lg_u64 s[36:37], 0
	s_cbranch_scc0 .Lmy_pfx_xb_0
	global_load_dwordx4 v[194:197], v[70:71], off
	global_load_dwordx4 v[198:201], v[70:71], off offset:1024
	global_load_dwordx4 v[202:205], v[70:71], off offset:2048
	global_load_dwordx4 v[206:209], v[70:71], off offset:3072
	s_branch .Lmy_pfx_done_0
.Lmy_pfx_xb_0:
	v_lshl_add_u64 v[190:191], v[66:67], 1, s[16:17]
	global_load_dwordx2 v[194:195], v[190:191], off
	global_load_dwordx2 v[198:199], v[190:191], off offset:512
	global_load_dwordx2 v[202:203], v[190:191], off offset:1024
	global_load_dwordx2 v[206:207], v[190:191], off offset:1536
.Lmy_pfx_done_0:
	s_and_saveexec_b64 s[2:3], s[36:37]
	s_xor_b64 s[2:3], exec, s[2:3]
	s_cbranch_execz .LBB0_638
	s_waitcnt vmcnt(0)
	v_mov_b32_e32 v36, v194
	v_mov_b32_e32 v37, v195
	v_mov_b32_e32 v38, v196
	v_mov_b32_e32 v39, v197
.LBB0_638:
	s_or_saveexec_b64 s[2:3], s[2:3]
	v_lshl_add_u64 v[84:85], v[66:67], 1, s[16:17]
	s_xor_b64 exec, exec, s[2:3]
	s_cbranch_execz .LBB0_640
	s_waitcnt vmcnt(0)
	v_mov_b32_e32 v38, v194
	v_mov_b32_e32 v39, v195
	s_waitcnt vmcnt(0)
	v_lshlrev_b32_e32 v36, 16, v38
	v_and_b32_e32 v37, 0xffff0000, v38
	v_lshlrev_b32_e32 v38, 16, v39
	v_and_b32_e32 v39, 0xffff0000, v39

; #define GAS __attribute__((address_space(1)))
; __device__ __forceinline__ void phase_ma(const Params& p, Frame& F, int l, const bool fd, const float* xin32) {
;     ...
;                     f32x4 xo; if (xin32) xo = *(const GAS f32x4*)(xin32 + (size_t)row * D + cc); else { const v2u xw = *(const GAS v2u*)(xb + (size_t)row * D + cc); xo = (f32x4){bf_lo(xw.x), bf_hi(xw.x), bf_lo(xw.y), bf_hi(xw.y)}; }
.LBB0_643:
	s_waitcnt vmcnt(0)
	v_mov_b32_e32 v36, v198
	v_mov_b32_e32 v37, v199
	v_mov_b32_e32 v38, v200
	v_mov_b32_e32 v39, v201
	s_andn2_saveexec_b64 s[14:15], s[14:15]
	s_cbranch_execnz .LBB0_647
	s_branch .LBB0_648

; #define GAS __attribute__((address_space(1)))
; __device__ __forceinline__ void phase_ma(const Params& p, Frame& F, int l, const bool fd, const float* xin32) {
;     ...
;                     if (special) y = *(const f32x4*)(y4096 + b * 1024 + cc); else { const v2u pw = *(const GAS v2u*)(P + cc), qw = *(const GAS v2u*)(P + 1024 + cc);
.LBB0_645:
	flat_load_dwordx4 v[32:35], v[54:55] offset:1024
	s_waitcnt vmcnt(0) lgkmcnt(0)
	s_and_saveexec_b64 s[14:15], s[36:37]
	s_xor_b64 s[14:15], exec, s[14:15]
	s_cbranch_execnz .LBB0_643

; #define GAS __attribute__((address_space(1)))
; __device__ __forceinline__ void phase_ma(const Params& p, Frame& F, int l, const bool fd, const float* xin32) {
;     ...
;                     f32x4 xo; if (xin32) xo = *(const GAS f32x4*)(xin32 + (size_t)row * D + cc); else { const v2u xw = *(const GAS v2u*)(xb + (size_t)row * D + cc); xo = (f32x4){bf_lo(xw.x), bf_hi(xw.x), bf_lo(xw.y), bf_hi(xw.y)}; }
.LBB0_647:
	s_waitcnt vmcnt(0)
	v_mov_b32_e32 v38, v198
	v_mov_b32_e32 v39, v199
	s_waitcnt vmcnt(0)
	v_lshlrev_b32_e32 v36, 16, v38
	v_and_b32_e32 v37, 0xffff0000, v38
	v_lshlrev_b32_e32 v38, 16, v39
	v_and_b32_e32 v39, 0xffff0000, v39

; #define GAS __attribute__((address_space(1)))
; __device__ __forceinline__ void phase_ma(const Params& p, Frame& F, int l, const bool fd, const float* xin32) {
;     ...
;                     f32x4 xo; if (xin32) xo = *(const GAS f32x4*)(xin32 + (size_t)row * D + cc); else { const v2u xw = *(const GAS v2u*)(xb + (size_t)row * D + cc); xo = (f32x4){bf_lo(xw.x), bf_hi(xw.x), bf_lo(xw.y), bf_hi(xw.y)}; }
.LBB0_651:
	s_waitcnt vmcnt(0)
	v_mov_b32_e32 v36, v202
	v_mov_b32_e32 v37, v203
	v_mov_b32_e32 v38, v204
	v_mov_b32_e32 v39, v205
	s_andn2_saveexec_b64 s[14:15], s[14:15]
	s_cbranch_execnz .LBB0_655
	s_branch .LBB0_656

; #define GAS __attribute__((address_space(1)))
; __device__ __forceinline__ void phase_ma(const Params& p, Frame& F, int l, const bool fd, const float* xin32) {
;     ...
;                     if (special) y = *(const f32x4*)(y4096 + b * 1024 + cc); else { const v2u pw = *(const GAS v2u*)(P + cc), qw = *(const GAS v2u*)(P + 1024 + cc);
.LBB0_653:
	flat_load_dwordx4 v[32:35], v[54:55] offset:2048
	s_waitcnt vmcnt(0) lgkmcnt(0)
	s_and_saveexec_b64 s[14:15], s[36:37]
	s_xor_b64 s[14:15], exec, s[14:15]
	s_cbranch_execnz .LBB0_651

; #define GAS __attribute__((address_space(1)))
; __device__ __forceinline__ void phase_ma(const Params& p, Frame& F, int l, const bool fd, const float* xin32) {
;     ...
;                     f32x4 xo; if (xin32) xo = *(const GAS f32x4*)(xin32 + (size_t)row * D + cc); else { const v2u xw = *(const GAS v2u*)(xb + (size_t)row * D + cc); xo = (f32x4){bf_lo(xw.x), bf_hi(xw.x), bf_lo(xw.y), bf_hi(xw.y)}; }
.LBB0_655:
	s_waitcnt vmcnt(0)
	v_mov_b32_e32 v38, v202
	v_mov_b32_e32 v39, v203
	s_waitcnt vmcnt(0)
	v_lshlrev_b32_e32 v36, 16, v38
	v_and_b32_e32 v37, 0xffff0000, v38
	v_lshlrev_b32_e32 v38, 16, v39
	v_and_b32_e32 v39, 0xffff0000, v39

; #define GAS __attribute__((address_space(1)))
; __device__ __forceinline__ void phase_ma(const Params& p, Frame& F, int l, const bool fd, const float* xin32) {
;     ...
;                     f32x4 xo; if (xin32) xo = *(const GAS f32x4*)(xin32 + (size_t)row * D + cc); else { const v2u xw = *(const GAS v2u*)(xb + (size_t)row * D + cc); xo = (f32x4){bf_lo(xw.x), bf_hi(xw.x), bf_lo(xw.y), bf_hi(xw.y)}; }
.LBB0_659:
	s_waitcnt vmcnt(0)
	v_mov_b32_e32 v36, v206
	v_mov_b32_e32 v37, v207
	v_mov_b32_e32 v38, v208
	v_mov_b32_e32 v39, v209
	s_andn2_saveexec_b64 s[2:3], s[2:3]
	s_cbranch_execnz .LBB0_663
	s_branch .LBB0_664

; #define GAS __attribute__((address_space(1)))
; __device__ __forceinline__ void phase_ma(const Params& p, Frame& F, int l, const bool fd, const float* xin32) {
;     ...
;                     if (special) y = *(const f32x4*)(y4096 + b * 1024 + cc); else { const v2u pw = *(const GAS v2u*)(P + cc), qw = *(const GAS v2u*)(P + 1024 + cc);
.LBB0_661:
	flat_load_dwordx4 v[32:35], v[54:55] offset:3072
	s_waitcnt vmcnt(0) lgkmcnt(0)
	s_and_saveexec_b64 s[2:3], s[36:37]
	s_xor_b64 s[2:3], exec, s[2:3]
	s_cbranch_execnz .LBB0_659

; #define GAS __attribute__((address_space(1)))
; __device__ __forceinline__ void phase_ma(const Params& p, Frame& F, int l, const bool fd, const float* xin32) {
;     ...
;                     f32x4 xo; if (xin32) xo = *(const GAS f32x4*)(xin32 + (size_t)row * D + cc); else { const v2u xw = *(const GAS v2u*)(xb + (size_t)row * D + cc); xo = (f32x4){bf_lo(xw.x), bf_hi(xw.x), bf_lo(xw.y), bf_hi(xw.y)}; }
.LBB0_663:
	s_waitcnt vmcnt(0)
	v_mov_b32_e32 v38, v206
	v_mov_b32_e32 v39, v207
	s_waitcnt vmcnt(0)
	v_lshlrev_b32_e32 v36, 16, v38
	v_and_b32_e32 v37, 0xffff0000, v38
	v_lshlrev_b32_e32 v38, 16, v39
	v_and_b32_e32 v39, 0xffff0000, v39

; #define GAS __attribute__((address_space(1)))
; __device__ __forceinline__ void phase_ma(const Params& p, Frame& F, int l, const bool fd, const float* xin32) {
;     ...
;             for (int j = 0; j < 4; ++j) { if (!fd) { const v2u xw = *(const GAS v2u*)(xb + (size_t)row * D + 256 * j + 4 * F.lane); h[r][j] = (f32x4){bf_lo(xw.x), bf_hi(xw.x), bf_lo(xw.y), bf_hi(xw.y)}; } ss += (h[r][j].x * h[r][j].x + h[r][j].y * h[r][j].y) + (h[r][j].z * h[r][j].z + h[r][j].w * h[r][j].w); }
.LBB0_666:
	s_waitcnt lgkmcnt(0)
	s_waitcnt vmcnt(0)
	v_mov_b32_e32 v34, v196
	v_mov_b32_e32 v35, v197
	s_nop 0
	v_lshlrev_b32_e32 v70, 16, v34
	v_and_b32_e32 v71, 0xffff0000, v34
	v_lshlrev_b32_e32 v104, 16, v35
	v_and_b32_e32 v105, 0xffff0000, v35
	s_and_b64 vcc, exec, s[48:49]
	s_cbranch_vccz .LBB0_617

; #define GAS __attribute__((address_space(1)))
; __device__ __forceinline__ void phase_ma(const Params& p, Frame& F, int l, const bool fd, const float* xin32) {
;     ...
;             for (int j = 0; j < 4; ++j) { if (!fd) { const v2u xw = *(const GAS v2u*)(xb + (size_t)row * D + 256 * j + 4 * F.lane); h[r][j] = (f32x4){bf_lo(xw.x), bf_hi(xw.x), bf_lo(xw.y), bf_hi(xw.y)}; } ss += (h[r][j].x * h[r][j].x + h[r][j].y * h[r][j].y) + (h[r][j].z * h[r][j].z + h[r][j].w * h[r][j].w); }
.LBB0_668:
	s_waitcnt vmcnt(0)
	v_mov_b32_e32 v32, v200
	v_mov_b32_e32 v33, v201
	s_nop 0
	v_lshlrev_b32_e32 v84, 16, v32
	v_and_b32_e32 v85, 0xffff0000, v32
	v_lshlrev_b32_e32 v126, 16, v33
	v_and_b32_e32 v127, 0xffff0000, v33

; #define GAS __attribute__((address_space(1)))
; __device__ __forceinline__ void phase_ma(const Params& p, Frame& F, int l, const bool fd, const float* xin32) {
;     ...
;             for (int j = 0; j < 4; ++j) { if (!fd) { const v2u xw = *(const GAS v2u*)(xb + (size_t)row * D + 256 * j + 4 * F.lane); h[r][j] = (f32x4){bf_lo(xw.x), bf_hi(xw.x), bf_lo(xw.y), bf_hi(xw.y)}; } ss += (h[r][j].x * h[r][j].x + h[r][j].y * h[r][j].y) + (h[r][j].z * h[r][j].z + h[r][j].w * h[r][j].w); }
.LBB0_672:
	s_waitcnt lgkmcnt(0)
	s_waitcnt vmcnt(0)
	v_mov_b32_e32 v34, v202
	v_mov_b32_e32 v35, v203
	s_nop 0
	v_lshlrev_b32_e32 v76, 16, v34
	v_and_b32_e32 v77, 0xffff0000, v34
	v_lshlrev_b32_e32 v110, 16, v35
	v_and_b32_e32 v111, 0xffff0000, v35
	s_and_b64 vcc, exec, s[48:49]
	s_cbranch_vccz .LBB0_723

; #define GAS __attribute__((address_space(1)))
; __device__ __forceinline__ void phase_ma(const Params& p, Frame& F, int l, const bool fd, const float* xin32) {
;     ...
;             for (int j = 0; j < 4; ++j) { if (!fd) { const v2u xw = *(const GAS v2u*)(xb + (size_t)row * D + 256 * j + 4 * F.lane); h[r][j] = (f32x4){bf_lo(xw.x), bf_hi(xw.x), bf_lo(xw.y), bf_hi(xw.y)}; } ss += (h[r][j].x * h[r][j].x + h[r][j].y * h[r][j].y) + (h[r][j].z * h[r][j].z + h[r][j].w * h[r][j].w); }
.LBB0_674:
	s_waitcnt lgkmcnt(0)
	s_waitcnt vmcnt(0)
	v_mov_b32_e32 v34, v206
	v_mov_b32_e32 v35, v207
	s_nop 0
	v_lshlrev_b32_e32 v72, 16, v34
	v_and_b32_e32 v73, 0xffff0000, v34
	v_lshlrev_b32_e32 v92, 16, v35
	v_and_b32_e32 v93, 0xffff0000, v35
	s_and_b64 vcc, exec, s[48:49]
	s_cbranch_vccnz .LBB0_726
	s_branch .LBB0_725

; #define GAS __attribute__((address_space(1)))
; __device__ __forceinline__ void phase_ma(const Params& p, Frame& F, int l, const bool fd, const float* xin32) {
;     ...
;                     if (special) y = *(const f32x4*)(y4096 + b * 1024 + cc); else { const v2u pw = *(const GAS v2u*)(P + cc), qw = *(const GAS v2u*)(P + 1024 + cc);
;                         y.x = bf_lo(pw.x) + sg * bf_lo(qw.x); y.y = bf_hi(pw.x) + sg * bf_hi(qw.x); y.z = bf_lo(pw.y) + sg * bf_lo(qw.y); y.w = bf_hi(pw.y) + sg * bf_hi(qw.y); }
;                     f32x4 xo; if (xin32) xo = *(const GAS f32x4*)(xin32 + (size_t)row * D + cc); else { const v2u xw = *(const GAS v2u*)(xb + (size_t)row * D + cc); xo = (f32x4){bf_lo(xw.x), bf_hi(xw.x), bf_lo(xw.y), bf_hi(xw.y)}; }
.LBB0_691:
	s_andn2_b64 vcc, exec, s[2:3]
	s_cbranch_vccnz .LBB0_693
	s_waitcnt lgkmcnt(0)
	flat_load_dwordx4 v[32:35], v[54:55]
	s_waitcnt vmcnt(0) lgkmcnt(0)
.LBB0_693:
	s_ashr_i32 s17, s16, 31
	s_lshl_b64 s[12:13], s[16:17], 11
	s_add_u32 s20, s6, s12
	s_addc_u32 s21, s7, s13
	s_lshl_b64 s[2:3], s[16:17], 12
	v_lshl_add_u64 v[36:37], v[64:65], 0, s[2:3]
	v_lshl_add_u64 v[74:75], v[66:67], 2, v[36:37]
	s_cmp_lg_u64 s[36:37], 0
	s_cbranch_scc0 .Lmy_pfx_xb_1
	global_load_dwordx4 v[194:197], v[74:75], off
	global_load_dwordx4 v[198:201], v[74:75], off offset:1024
	global_load_dwordx4 v[202:205], v[74:75], off offset:2048
	global_load_dwordx4 v[206:209], v[74:75], off offset:3072
	s_branch .Lmy_pfx_done_1
.Lmy_pfx_xb_1:
	v_lshl_add_u64 v[190:191], v[66:67], 1, s[20:21]
	global_load_dwordx2 v[194:195], v[190:191], off
	global_load_dwordx2 v[198:199], v[190:191], off offset:512
	global_load_dwordx2 v[202:203], v[190:191], off offset:1024
	global_load_dwordx2 v[206:207], v[190:191], off offset:1536

; #define GAS __attribute__((address_space(1)))
; __device__ __forceinline__ void phase_ma(const Params& p, Frame& F, int l, const bool fd, const float* xin32) {
;     ...
;                     f32x4 xo; if (xin32) xo = *(const GAS f32x4*)(xin32 + (size_t)row * D + cc); else { const v2u xw = *(const GAS v2u*)(xb + (size_t)row * D + cc); xo = (f32x4){bf_lo(xw.x), bf_hi(xw.x), bf_lo(xw.y), bf_hi(xw.y)}; }
.LBB0_695:
	s_or_saveexec_b64 s[2:3], s[2:3]
	v_lshl_add_u64 v[94:95], v[66:67], 1, s[20:21]
	s_xor_b64 exec, exec, s[2:3]
	s_cbranch_execz .LBB0_697
	s_waitcnt vmcnt(0)
	v_mov_b32_e32 v38, v194
	v_mov_b32_e32 v39, v195
	s_waitcnt vmcnt(0)
	v_lshlrev_b32_e32 v36, 16, v38
	v_and_b32_e32 v37, 0xffff0000, v38
	v_lshlrev_b32_e32 v38, 16, v39
	v_and_b32_e32 v39, 0xffff0000, v39

; #define GAS __attribute__((address_space(1)))
; __device__ __forceinline__ void phase_ma(const Params& p, Frame& F, int l, const bool fd, const float* xin32) {
;     ...
;                     f32x4 xo; if (xin32) xo = *(const GAS f32x4*)(xin32 + (size_t)row * D + cc); else { const v2u xw = *(const GAS v2u*)(xb + (size_t)row * D + cc); xo = (f32x4){bf_lo(xw.x), bf_hi(xw.x), bf_lo(xw.y), bf_hi(xw.y)}; }
.LBB0_700:
	s_waitcnt vmcnt(0)
	v_mov_b32_e32 v36, v198
	v_mov_b32_e32 v37, v199
	v_mov_b32_e32 v38, v200
	v_mov_b32_e32 v39, v201
	s_andn2_saveexec_b64 s[16:17], s[16:17]
	s_cbranch_execnz .LBB0_704
	s_branch .LBB0_705

; #define GAS __attribute__((address_space(1)))
; __device__ __forceinline__ void phase_ma(const Params& p, Frame& F, int l, const bool fd, const float* xin32) {
;     ...
;                     if (special) y = *(const f32x4*)(y4096 + b * 1024 + cc); else { const v2u pw = *(const GAS v2u*)(P + cc), qw = *(const GAS v2u*)(P + 1024 + cc);
.LBB0_702:
	flat_load_dwordx4 v[32:35], v[54:55] offset:1024
	s_waitcnt vmcnt(0) lgkmcnt(0)
	s_and_saveexec_b64 s[16:17], s[36:37]
	s_xor_b64 s[16:17], exec, s[16:17]
	s_cbranch_execnz .LBB0_700

; #define GAS __attribute__((address_space(1)))
; __device__ __forceinline__ void phase_ma(const Params& p, Frame& F, int l, const bool fd, const float* xin32) {
;     ...
;                     f32x4 xo; if (xin32) xo = *(const GAS f32x4*)(xin32 + (size_t)row * D + cc); else { const v2u xw = *(const GAS v2u*)(xb + (size_t)row * D + cc); xo = (f32x4){bf_lo(xw.x), bf_hi(xw.x), bf_lo(xw.y), bf_hi(xw.y)}; }
.LBB0_708:
	s_waitcnt vmcnt(0)
	v_mov_b32_e32 v36, v202
	v_mov_b32_e32 v37, v203
	v_mov_b32_e32 v38, v204
	v_mov_b32_e32 v39, v205
	s_andn2_saveexec_b64 s[16:17], s[16:17]
	s_cbranch_execnz .LBB0_712
	s_branch .LBB0_713

; #define GAS __attribute__((address_space(1)))
; __device__ __forceinline__ void phase_ma(const Params& p, Frame& F, int l, const bool fd, const float* xin32) {
;     ...
;                     if (special) y = *(const f32x4*)(y4096 + b * 1024 + cc); else { const v2u pw = *(const GAS v2u*)(P + cc), qw = *(const GAS v2u*)(P + 1024 + cc);
.LBB0_710:
	flat_load_dwordx4 v[32:35], v[54:55] offset:2048
	s_waitcnt vmcnt(0) lgkmcnt(0)
	s_and_saveexec_b64 s[16:17], s[36:37]
	s_xor_b64 s[16:17], exec, s[16:17]
	s_cbranch_execnz .LBB0_708

; #define GAS __attribute__((address_space(1)))
; __device__ __forceinline__ void phase_ma(const Params& p, Frame& F, int l, const bool fd, const float* xin32) {
;     ...
;             for (int j = 0; j < 4; ++j) { if (!fd) { const v2u xw = *(const GAS v2u*)(xb + (size_t)row * D + 256 * j + 4 * F.lane); h[r][j] = (f32x4){bf_lo(xw.x), bf_hi(xw.x), bf_lo(xw.y), bf_hi(xw.y)}; } ss += (h[r][j].x * h[r][j].x + h[r][j].y * h[r][j].y) + (h[r][j].z * h[r][j].z + h[r][j].w * h[r][j].w); }
.LBB0_723:
	s_waitcnt lgkmcnt(0)
	s_waitcnt vmcnt(0)
	v_mov_b32_e32 v34, v204
	v_mov_b32_e32 v35, v205
	s_nop 0
	v_lshlrev_b32_e32 v74, 16, v34
	v_and_b32_e32 v75, 0xffff0000, v34
	v_lshlrev_b32_e32 v102, 16, v35
	v_and_b32_e32 v103, 0xffff0000, v35
	s_and_b64 vcc, exec, s[48:49]
	s_cbranch_vccz .LBB0_674

; #define GAS __attribute__((address_space(1)))
; __device__ __forceinline__ void phase_ma(const Params& p, Frame& F, int l, const bool fd, const float* xin32) {
;     ...
;             for (int j = 0; j < 4; ++j) { if (!fd) { const v2u xw = *(const GAS v2u*)(xb + (size_t)row * D + 256 * j + 4 * F.lane); h[r][j] = (f32x4){bf_lo(xw.x), bf_hi(xw.x), bf_lo(xw.y), bf_hi(xw.y)}; } ss += (h[r][j].x * h[r][j].x + h[r][j].y * h[r][j].y) + (h[r][j].z * h[r][j].z + h[r][j].w * h[r][j].w); }
.LBB0_725:
	s_waitcnt vmcnt(0)
	v_mov_b32_e32 v32, v208
	v_mov_b32_e32 v33, v209
	s_nop 0
	v_lshlrev_b32_e32 v94, 16, v32
	v_and_b32_e32 v95, 0xffff0000, v32
	v_lshlrev_b32_e32 v124, 16, v33
	v_and_b32_e32 v125, 0xffff0000, v33

; #define GAS __attribute__((address_space(1)))
; __device__ __forceinline__ void phase_ma(const Params& p, Frame& F, int l, const bool fd, const float* xin32) {
;     ...
;             for (int j = 0; j < 4; ++j) { if (!fd) { const v2u xw = *(const GAS v2u*)(xb + (size_t)row * D + 256 * j + 4 * F.lane); h[r][j] = (f32x4){bf_lo(xw.x), bf_hi(xw.x), bf_lo(xw.y), bf_hi(xw.y)}; } ss += (h[r][j].x * h[r][j].x + h[r][j].y * h[r][j].y) + (h[r][j].z * h[r][j].z + h[r][j].w * h[r][j].w); }
.LBB0_729:
	s_waitcnt lgkmcnt(0)
	s_waitcnt vmcnt(0)
	v_mov_b32_e32 v34, v210
	v_mov_b32_e32 v35, v211
	s_nop 0
	v_lshlrev_b32_e32 v86, 16, v34
	v_and_b32_e32 v87, 0xffff0000, v34
	v_lshlrev_b32_e32 v116, 16, v35
	v_and_b32_e32 v117, 0xffff0000, v35
	s_and_b64 vcc, exec, s[48:49]
	s_cbranch_vccz .LBB0_780

; #define GAS __attribute__((address_space(1)))
; __device__ __forceinline__ void phase_ma(const Params& p, Frame& F, int l, const bool fd, const float* xin32) {
;     ...
;             for (int j = 0; j < 4; ++j) { if (!fd) { const v2u xw = *(const GAS v2u*)(xb + (size_t)row * D + 256 * j + 4 * F.lane); h[r][j] = (f32x4){bf_lo(xw.x), bf_hi(xw.x), bf_lo(xw.y), bf_hi(xw.y)}; } ss += (h[r][j].x * h[r][j].x + h[r][j].y * h[r][j].y) + (h[r][j].z * h[r][j].z + h[r][j].w * h[r][j].w); }
.LBB0_731:
	s_waitcnt lgkmcnt(0)
	s_waitcnt vmcnt(0)
	v_mov_b32_e32 v34, v214
	v_mov_b32_e32 v35, v215
	s_nop 0
	v_lshlrev_b32_e32 v80, 16, v34
	v_and_b32_e32 v81, 0xffff0000, v34
	v_lshlrev_b32_e32 v100, 16, v35
	v_and_b32_e32 v101, 0xffff0000, v35
	s_and_b64 vcc, exec, s[48:49]
	s_cbranch_vccnz .LBB0_783
	s_branch .LBB0_782

; #define GAS __attribute__((address_space(1)))
; __device__ __forceinline__ void phase_ma(const Params& p, Frame& F, int l, const bool fd, const float* xin32) {
;     ...
;                     f32x4 xo; if (xin32) xo = *(const GAS f32x4*)(xin32 + (size_t)row * D + cc); else { const v2u xw = *(const GAS v2u*)(xb + (size_t)row * D + cc); xo = (f32x4){bf_lo(xw.x), bf_hi(xw.x), bf_lo(xw.y), bf_hi(xw.y)}; }
.LBB0_750:
	s_ashr_i32 s19, s18, 31
	s_lshl_b64 s[14:15], s[18:19], 11
	s_add_u32 s22, s6, s14
	s_addc_u32 s23, s7, s15
	s_lshl_b64 s[2:3], s[18:19], 12
	v_lshl_add_u64 v[36:37], v[64:65], 0, s[2:3]
	v_lshl_add_u64 v[82:83], v[66:67], 2, v[36:37]
	s_cmp_lg_u64 s[36:37], 0
	s_cbranch_scc0 .Lmy_pfx_xb_2
	global_load_dwordx4 v[194:197], v[82:83], off
	global_load_dwordx4 v[198:201], v[82:83], off offset:1024
	global_load_dwordx4 v[202:205], v[82:83], off offset:2048
	global_load_dwordx4 v[206:209], v[82:83], off offset:3072
	s_branch .Lmy_pfx_done_2
.Lmy_pfx_xb_2:
	v_lshl_add_u64 v[190:191], v[66:67], 1, s[22:23]
	global_load_dwordx2 v[194:195], v[190:191], off
	global_load_dwordx2 v[198:199], v[190:191], off offset:512
	global_load_dwordx2 v[202:203], v[190:191], off offset:1024
	global_load_dwordx2 v[206:207], v[190:191], off offset:1536

; #define GAS __attribute__((address_space(1)))
; __device__ __forceinline__ void phase_ma(const Params& p, Frame& F, int l, const bool fd, const float* xin32) {
;     ...
;                     f32x4 xo; if (xin32) xo = *(const GAS f32x4*)(xin32 + (size_t)row * D + cc); else { const v2u xw = *(const GAS v2u*)(xb + (size_t)row * D + cc); xo = (f32x4){bf_lo(xw.x), bf_hi(xw.x), bf_lo(xw.y), bf_hi(xw.y)}; }
.LBB0_752:
	s_or_saveexec_b64 s[2:3], s[2:3]
	v_lshl_add_u64 v[114:115], v[66:67], 1, s[22:23]
	s_xor_b64 exec, exec, s[2:3]
	s_cbranch_execz .LBB0_754
	s_waitcnt vmcnt(0)
	v_mov_b32_e32 v38, v194
	v_mov_b32_e32 v39, v195
	s_waitcnt vmcnt(0)
	v_lshlrev_b32_e32 v36, 16, v38
	v_and_b32_e32 v37, 0xffff0000, v38
	v_lshlrev_b32_e32 v38, 16, v39
	v_and_b32_e32 v39, 0xffff0000, v39

; #define GAS __attribute__((address_space(1)))
; __device__ __forceinline__ void phase_ma(const Params& p, Frame& F, int l, const bool fd, const float* xin32) {
;     ...
;                     f32x4 xo; if (xin32) xo = *(const GAS f32x4*)(xin32 + (size_t)row * D + cc); else { const v2u xw = *(const GAS v2u*)(xb + (size_t)row * D + cc); xo = (f32x4){bf_lo(xw.x), bf_hi(xw.x), bf_lo(xw.y), bf_hi(xw.y)}; }
.LBB0_757:
	s_waitcnt vmcnt(0)
	v_mov_b32_e32 v36, v198
	v_mov_b32_e32 v37, v199
	v_mov_b32_e32 v38, v200
	v_mov_b32_e32 v39, v201
	s_andn2_saveexec_b64 s[18:19], s[18:19]
	s_cbranch_execnz .LBB0_761
	s_branch .LBB0_762

; #define GAS __attribute__((address_space(1)))
; __device__ __forceinline__ void phase_ma(const Params& p, Frame& F, int l, const bool fd, const float* xin32) {
;     ...
;                     if (special) y = *(const f32x4*)(y4096 + b * 1024 + cc); else { const v2u pw = *(const GAS v2u*)(P + cc), qw = *(const GAS v2u*)(P + 1024 + cc);
.LBB0_759:
	flat_load_dwordx4 v[32:35], v[54:55] offset:1024
	s_waitcnt vmcnt(0) lgkmcnt(0)
	s_and_saveexec_b64 s[18:19], s[36:37]
	s_xor_b64 s[18:19], exec, s[18:19]
	s_cbranch_execnz .LBB0_757

; #define GAS __attribute__((address_space(1)))
; __device__ __forceinline__ void phase_ma(const Params& p, Frame& F, int l, const bool fd, const float* xin32) {
;     ...
;                     f32x4 xo; if (xin32) xo = *(const GAS f32x4*)(xin32 + (size_t)row * D + cc); else { const v2u xw = *(const GAS v2u*)(xb + (size_t)row * D + cc); xo = (f32x4){bf_lo(xw.x), bf_hi(xw.x), bf_lo(xw.y), bf_hi(xw.y)}; }
.LBB0_765:
	s_waitcnt vmcnt(0)
	v_mov_b32_e32 v36, v202
	v_mov_b32_e32 v37, v203
	v_mov_b32_e32 v38, v204
	v_mov_b32_e32 v39, v205
	s_andn2_saveexec_b64 s[18:19], s[18:19]
	s_cbranch_execnz .LBB0_769
	s_branch .LBB0_770

; #define GAS __attribute__((address_space(1)))
; __device__ __forceinline__ void phase_ma(const Params& p, Frame& F, int l, const bool fd, const float* xin32) {
;     ...
;                     if (special) y = *(const f32x4*)(y4096 + b * 1024 + cc); else { const v2u pw = *(const GAS v2u*)(P + cc), qw = *(const GAS v2u*)(P + 1024 + cc);
.LBB0_767:
	flat_load_dwordx4 v[32:35], v[54:55] offset:2048
	s_waitcnt vmcnt(0) lgkmcnt(0)
	s_and_saveexec_b64 s[18:19], s[36:37]
	s_xor_b64 s[18:19], exec, s[18:19]
	s_cbranch_execnz .LBB0_765

; #define GAS __attribute__((address_space(1)))
; __device__ __forceinline__ void phase_ma(const Params& p, Frame& F, int l, const bool fd, const float* xin32) {
;     ...
;             for (int j = 0; j < 4; ++j) { if (!fd) { const v2u xw = *(const GAS v2u*)(xb + (size_t)row * D + 256 * j + 4 * F.lane); h[r][j] = (f32x4){bf_lo(xw.x), bf_hi(xw.x), bf_lo(xw.y), bf_hi(xw.y)}; } ss += (h[r][j].x * h[r][j].x + h[r][j].y * h[r][j].y) + (h[r][j].z * h[r][j].z + h[r][j].w * h[r][j].w); }
.LBB0_780:
	s_waitcnt lgkmcnt(0)
	s_waitcnt vmcnt(0)
	v_mov_b32_e32 v34, v212
	v_mov_b32_e32 v35, v213
	s_nop 0
	v_lshlrev_b32_e32 v82, 16, v34
	v_and_b32_e32 v83, 0xffff0000, v34
	v_lshlrev_b32_e32 v106, 16, v35
	v_and_b32_e32 v107, 0xffff0000, v35
	s_and_b64 vcc, exec, s[48:49]
	s_cbranch_vccz .LBB0_731

; #define GAS __attribute__((address_space(1)))
; __device__ __forceinline__ void phase_ma(const Params& p, Frame& F, int l, const bool fd, const float* xin32) {
;     ...
;             for (int j = 0; j < 4; ++j) { if (!fd) { const v2u xw = *(const GAS v2u*)(xb + (size_t)row * D + 256 * j + 4 * F.lane); h[r][j] = (f32x4){bf_lo(xw.x), bf_hi(xw.x), bf_lo(xw.y), bf_hi(xw.y)}; } ss += (h[r][j].x * h[r][j].x + h[r][j].y * h[r][j].y) + (h[r][j].z * h[r][j].z + h[r][j].w * h[r][j].w); }
.LBB0_782:
	s_waitcnt vmcnt(0)
	v_mov_b32_e32 v32, v216
	v_mov_b32_e32 v33, v217
	s_nop 0
	v_lshlrev_b32_e32 v114, 16, v32
	v_and_b32_e32 v115, 0xffff0000, v32
	v_lshlrev_b32_e32 v128, 16, v33
	v_and_b32_e32 v129, 0xffff0000, v33

; #define GAS __attribute__((address_space(1)))
; __device__ __forceinline__ void phase_ma(const Params& p, Frame& F, int l, const bool fd, const float* xin32) {
;     ...
;             for (int j = 0; j < 4; ++j) { if (!fd) { const v2u xw = *(const GAS v2u*)(xb + (size_t)row * D + 256 * j + 4 * F.lane); h[r][j] = (f32x4){bf_lo(xw.x), bf_hi(xw.x), bf_lo(xw.y), bf_hi(xw.y)}; } ss += (h[r][j].x * h[r][j].x + h[r][j].y * h[r][j].y) + (h[r][j].z * h[r][j].z + h[r][j].w * h[r][j].w); }
.LBB0_786:
	s_waitcnt lgkmcnt(0)
	s_waitcnt vmcnt(0)
	v_mov_b32_e32 v34, v218
	v_mov_b32_e32 v35, v219
	s_nop 0
	v_lshlrev_b32_e32 v98, 16, v34
	v_and_b32_e32 v99, 0xffff0000, v34
	v_lshlrev_b32_e32 v120, 16, v35
	v_and_b32_e32 v121, 0xffff0000, v35
	s_and_b64 vcc, exec, s[48:49]
	s_cbranch_vccz .LBB0_837

; #define GAS __attribute__((address_space(1)))
; __device__ __forceinline__ void phase_ma(const Params& p, Frame& F, int l, const bool fd, const float* xin32) {
;     ...
;             for (int j = 0; j < 4; ++j) { if (!fd) { const v2u xw = *(const GAS v2u*)(xb + (size_t)row * D + 256 * j + 4 * F.lane); h[r][j] = (f32x4){bf_lo(xw.x), bf_hi(xw.x), bf_lo(xw.y), bf_hi(xw.y)}; } ss += (h[r][j].x * h[r][j].x + h[r][j].y * h[r][j].y) + (h[r][j].z * h[r][j].z + h[r][j].w * h[r][j].w); }
.LBB0_788:
	s_waitcnt lgkmcnt(0)
	s_waitcnt vmcnt(0)
	v_mov_b32_e32 v34, v222
	v_mov_b32_e32 v35, v223
	s_nop 0
	v_lshlrev_b32_e32 v88, 16, v34
	v_and_b32_e32 v89, 0xffff0000, v34
	v_lshlrev_b32_e32 v108, 16, v35
	v_and_b32_e32 v109, 0xffff0000, v35
	s_and_b64 vcc, exec, s[48:49]
	s_cbranch_vccz .LBB0_839
	s_branch .LBB0_840

; #define GAS __attribute__((address_space(1)))
; __device__ __forceinline__ void phase_ma(const Params& p, Frame& F, int l, const bool fd, const float* xin32) {
;     ...
;                     f32x4 xo; if (xin32) xo = *(const GAS f32x4*)(xin32 + (size_t)row * D + cc); else { const v2u xw = *(const GAS v2u*)(xb + (size_t)row * D + cc); xo = (f32x4){bf_lo(xw.x), bf_hi(xw.x), bf_lo(xw.y), bf_hi(xw.y)}; }
.LBB0_807:
	s_ashr_i32 s21, s20, 31
	s_lshl_b64 s[16:17], s[20:21], 11
	s_add_u32 s24, s6, s16
	s_addc_u32 s25, s7, s17
	s_lshl_b64 s[2:3], s[20:21], 12
	v_lshl_add_u64 v[36:37], v[64:65], 0, s[2:3]
	v_lshl_add_u64 v[90:91], v[66:67], 2, v[36:37]
	s_cmp_lg_u64 s[36:37], 0
	s_cbranch_scc0 .Lmy_pfx_xb_3
	global_load_dwordx4 v[194:197], v[90:91], off
	global_load_dwordx4 v[198:201], v[90:91], off offset:1024
	global_load_dwordx4 v[202:205], v[90:91], off offset:2048
	global_load_dwordx4 v[206:209], v[90:91], off offset:3072
	s_branch .Lmy_pfx_done_3
.Lmy_pfx_xb_3:
	v_lshl_add_u64 v[190:191], v[66:67], 1, s[24:25]
	global_load_dwordx2 v[194:195], v[190:191], off
	global_load_dwordx2 v[198:199], v[190:191], off offset:512
	global_load_dwordx2 v[202:203], v[190:191], off offset:1024
	global_load_dwordx2 v[206:207], v[190:191], off offset:1536

; #define GAS __attribute__((address_space(1)))
; __device__ __forceinline__ void phase_ma(const Params& p, Frame& F, int l, const bool fd, const float* xin32) {
;     ...
;                     f32x4 xo; if (xin32) xo = *(const GAS f32x4*)(xin32 + (size_t)row * D + cc); else { const v2u xw = *(const GAS v2u*)(xb + (size_t)row * D + cc); xo = (f32x4){bf_lo(xw.x), bf_hi(xw.x), bf_lo(xw.y), bf_hi(xw.y)}; }
.LBB0_809:
	s_or_saveexec_b64 s[2:3], s[2:3]
	v_lshl_add_u64 v[122:123], v[66:67], 1, s[24:25]
	s_xor_b64 exec, exec, s[2:3]
	s_cbranch_execz .LBB0_811
	s_waitcnt vmcnt(0)
	v_mov_b32_e32 v38, v194
	v_mov_b32_e32 v39, v195
	s_waitcnt vmcnt(0)
	v_lshlrev_b32_e32 v36, 16, v38
	v_and_b32_e32 v37, 0xffff0000, v38
	v_lshlrev_b32_e32 v38, 16, v39
	v_and_b32_e32 v39, 0xffff0000, v39

; #define GAS __attribute__((address_space(1)))
; __device__ __forceinline__ void phase_ma(const Params& p, Frame& F, int l, const bool fd, const float* xin32) {
;     ...
;                     f32x4 xo; if (xin32) xo = *(const GAS f32x4*)(xin32 + (size_t)row * D + cc); else { const v2u xw = *(const GAS v2u*)(xb + (size_t)row * D + cc); xo = (f32x4){bf_lo(xw.x), bf_hi(xw.x), bf_lo(xw.y), bf_hi(xw.y)}; }
.LBB0_814:
	s_waitcnt vmcnt(0)
	v_mov_b32_e32 v36, v198
	v_mov_b32_e32 v37, v199
	v_mov_b32_e32 v38, v200
	v_mov_b32_e32 v39, v201
	s_andn2_saveexec_b64 s[20:21], s[20:21]
	s_cbranch_execnz .LBB0_818
	s_branch .LBB0_819

; #define GAS __attribute__((address_space(1)))
; __device__ __forceinline__ void phase_ma(const Params& p, Frame& F, int l, const bool fd, const float* xin32) {
;     ...
;                     if (special) y = *(const f32x4*)(y4096 + b * 1024 + cc); else { const v2u pw = *(const GAS v2u*)(P + cc), qw = *(const GAS v2u*)(P + 1024 + cc);
.LBB0_816:
	flat_load_dwordx4 v[32:35], v[54:55] offset:1024
	s_waitcnt vmcnt(0) lgkmcnt(0)
	s_and_saveexec_b64 s[20:21], s[36:37]
	s_xor_b64 s[20:21], exec, s[20:21]
	s_cbranch_execnz .LBB0_814

; #define GAS __attribute__((address_space(1)))
; __device__ __forceinline__ void phase_ma(const Params& p, Frame& F, int l, const bool fd, const float* xin32) {
;     ...
;                     f32x4 xo; if (xin32) xo = *(const GAS f32x4*)(xin32 + (size_t)row * D + cc); else { const v2u xw = *(const GAS v2u*)(xb + (size_t)row * D + cc); xo = (f32x4){bf_lo(xw.x), bf_hi(xw.x), bf_lo(xw.y), bf_hi(xw.y)}; }
.LBB0_822:
	s_waitcnt vmcnt(0)
	v_mov_b32_e32 v36, v202
	v_mov_b32_e32 v37, v203
	v_mov_b32_e32 v38, v204
	v_mov_b32_e32 v39, v205
	s_andn2_saveexec_b64 s[20:21], s[20:21]
	s_cbranch_execnz .LBB0_826
	s_branch .LBB0_827

; #define GAS __attribute__((address_space(1)))
; __device__ __forceinline__ void phase_ma(const Params& p, Frame& F, int l, const bool fd, const float* xin32) {
;     ...
;                     if (special) y = *(const f32x4*)(y4096 + b * 1024 + cc); else { const v2u pw = *(const GAS v2u*)(P + cc), qw = *(const GAS v2u*)(P + 1024 + cc);
.LBB0_824:
	flat_load_dwordx4 v[32:35], v[54:55] offset:2048
	s_waitcnt vmcnt(0) lgkmcnt(0)
	s_and_saveexec_b64 s[20:21], s[36:37]
	s_xor_b64 s[20:21], exec, s[20:21]
	s_cbranch_execnz .LBB0_822

; #define GAS __attribute__((address_space(1)))
; __device__ __forceinline__ void phase_ma(const Params& p, Frame& F, int l, const bool fd, const float* xin32) {
;     ...
;             for (int j = 0; j < 4; ++j) { if (!fd) { const v2u xw = *(const GAS v2u*)(xb + (size_t)row * D + 256 * j + 4 * F.lane); h[r][j] = (f32x4){bf_lo(xw.x), bf_hi(xw.x), bf_lo(xw.y), bf_hi(xw.y)}; } ss += (h[r][j].x * h[r][j].x + h[r][j].y * h[r][j].y) + (h[r][j].z * h[r][j].z + h[r][j].w * h[r][j].w); }
.LBB0_837:
	s_waitcnt lgkmcnt(0)
	s_waitcnt vmcnt(0)
	v_mov_b32_e32 v34, v220
	v_mov_b32_e32 v35, v221
	s_nop 0
	v_lshlrev_b32_e32 v90, 16, v34
	v_and_b32_e32 v91, 0xffff0000, v34
	v_lshlrev_b32_e32 v118, 16, v35
	v_and_b32_e32 v119, 0xffff0000, v35
	s_and_b64 vcc, exec, s[48:49]
	s_cbranch_vccz .LBB0_788

; #define GAS __attribute__((address_space(1)))
; __device__ __forceinline__ void phase_ma(const Params& p, Frame& F, int l, const bool fd, const float* xin32) {
;     ...
;             for (int j = 0; j < 4; ++j) { if (!fd) { const v2u xw = *(const GAS v2u*)(xb + (size_t)row * D + 256 * j + 4 * F.lane); h[r][j] = (f32x4){bf_lo(xw.x), bf_hi(xw.x), bf_lo(xw.y), bf_hi(xw.y)}; } ss += (h[r][j].x * h[r][j].x + h[r][j].y * h[r][j].y) + (h[r][j].z * h[r][j].z + h[r][j].w * h[r][j].w); }
.LBB0_839:
	s_waitcnt vmcnt(0)
	v_mov_b32_e32 v32, v224
	v_mov_b32_e32 v33, v225
	s_nop 0
	v_lshlrev_b32_e32 v122, 16, v32
	v_and_b32_e32 v123, 0xffff0000, v32
	v_lshlrev_b32_e32 v130, 16, v33
	v_and_b32_e32 v131, 0xffff0000, v33
